# FFN1-down residual epilogue also fused with its rmsnorm+modulate phase (third fused norm); two norm phases, the final norm and three grid barriers removed in total
# speedup vs baseline: 1.0076x; 1.0018x over previous
.LBB0_285:
	s_lshl_b32 s0, s87, 9
	v_add_u32_e32 v0, s0, v230
	v_mov_b32_e32 v1, 0x100
	v_cmp_gt_u32_e32 vcc, v1, v0
	s_and_saveexec_b64 s[2:3], vcc
	s_load_dwordx2 s[0:1], s[92:93], 0xd8
	v_lshlrev_b32_e32 v0, 2, v0
	v_mov_b32_e32 v1, 0
	s_waitcnt lgkmcnt(0)
	s_add_u32 s0, s0, 0x33a0800
	s_addc_u32 s1, s1, 0
	global_store_dword v0, v1, s[0:1]
	s_or_b64 exec, exec, s[2:3]
	s_waitcnt vmcnt(0)
	s_waitcnt vmcnt(0)
	s_barrier
	s_mov_b64 s[0:1], exec
	v_readlane_b32 s2, v252, 2
	v_readlane_b32 s3, v252, 3
	s_and_b64 s[2:3], s[0:1], s[2:3]
	s_mov_b64 exec, s[2:3]
	s_cbranch_execz .LBB0_337
	s_add_i32 s2, 0, 0x20040
	v_mov_b32_e32 v0, s2
	s_waitcnt vmcnt(0) expcnt(0) lgkmcnt(0)
	ds_read_b32 v2, v0
	s_add_i32 s2, 0, 0x20044
	v_mov_b32_e32 v0, s2
	ds_read_b32 v0, v0
	s_waitcnt lgkmcnt(1)
	v_cmp_ne_u32_e32 vcc, 0, v2
	s_cbranch_vccnz .LBB0_301
	s_add_u32 s4, s88, 0x1000
	s_addc_u32 s5, s89, 0
	s_add_u32 s6, s88, 0x1100
	s_addc_u32 s7, s89, 0
	s_add_u32 s8, s88, 0x1200
	v_readlane_b32 s2, v252, 0
	s_addc_u32 s9, s89, 0
	s_mul_i32 s2, s91, s2
	s_add_u32 s10, s88, 0x1300
	s_mul_i32 s2, s2, s90
	s_addc_u32 s11, s89, 0
	s_mov_b32 s3, 1
	v_mov_b32_e32 v16, 0
	s_branch .LBB0_289

.LBB0_361:
	s_mov_b32 s36, s69
	s_mov_b32 s37, s70
	v_lshl_add_u32 v128, s69, 8, v221
	v_lshl_or_b32 v136, s70, 8, v223
	s_load_dwordx2 s[22:23], s[92:93], 0x48
	s_load_dwordx2 s[24:25], s[92:93], 0xd8
	s_ashr_i32 s2, s69, 4
	v_lshlrev_b32_e32 v136, 2, v136
	s_mul_hi_i32 s32, s2, 0x9000
	s_mul_i32 s2, s2, 0x9000
	v_lshl_add_u32 v128, v128, 12, v136
	s_add_u32 s34, s52, s2
	s_addc_u32 s35, s53, s32
	v_add_u32_e32 v129, 0x10000, v128
	v_add_u32_e32 v130, 0x20000, v128
	v_add_u32_e32 v131, 0x30000, v128
	v_add_u32_e32 v132, 0x80000, v128
	v_add_u32_e32 v133, 0x90000, v128
	v_add_u32_e32 v134, 0xa0000, v128
	v_add_u32_e32 v135, 0xb0000, v128
	v_and_b32_e32 v137, 63, v230
	v_xor_b32_e32 v138, 32, v137
	v_xor_b32_e32 v137, 16, v137
	v_lshlrev_b32_e32 v138, 2, v138
	v_lshlrev_b32_e32 v137, 2, v137
	global_load_dwordx4 v[140:143], v136, s[34:35]
	global_load_dwordx4 v[144:147], v136, s[34:35] offset:64
	global_load_dwordx4 v[148:151], v136, s[34:35] offset:512
	global_load_dwordx4 v[152:155], v136, s[34:35] offset:576
	global_load_dwordx4 v[188:191], v128, s[0:1]
	global_load_dwordx4 v[192:195], v128, s[0:1] offset:64
	global_load_dwordx4 v[196:199], v128, s[0:1] offset:512
	global_load_dwordx4 v[200:203], v128, s[0:1] offset:576
	global_load_dwordx4 v[204:207], v129, s[0:1]
	global_load_dwordx4 v[208:211], v129, s[0:1] offset:64
	global_load_dwordx4 v[212:215], v129, s[0:1] offset:512
	global_load_dwordx4 v[216:219], v129, s[0:1] offset:576
	global_load_dwordx4 v[156:159], v130, s[0:1]
	global_load_dwordx4 v[160:163], v130, s[0:1] offset:64
	global_load_dwordx4 v[164:167], v130, s[0:1] offset:512
	global_load_dwordx4 v[168:171], v130, s[0:1] offset:576
	global_load_dwordx4 v[232:235], v131, s[0:1]
	global_load_dwordx4 v[236:239], v131, s[0:1] offset:64
	global_load_dwordx4 v[240:243], v131, s[0:1] offset:512
	global_load_dwordx4 v[244:247], v131, s[0:1] offset:576
	s_waitcnt lgkmcnt(0)
	s_add_u32 s72, s24, 0x3010000
	s_addc_u32 s73, s25, 0
	s_add_u32 s72, s72, s2
	s_addc_u32 s73, s73, s32
	s_add_u32 s76, s72, 0x4000
	s_addc_u32 s77, s73, 0
	s_add_u32 s78, s72, 0x3000
	s_addc_u32 s79, s73, 0
	s_add_u32 s74, s24, 0x86a0000
	s_addc_u32 s75, s25, 0
	s_add_u32 s24, s24, 0x32a0000
	s_addc_u32 s25, s25, 0
	s_add_u32 s26, s24, 0x100800
	s_addc_u32 s27, s25, 0
	s_waitcnt vmcnt(8)
	v_pk_mul_f32 v[140:141], v[140:141], 0.5 op_sel_hi:[1,0]
	v_pk_mul_f32 v[142:143], v[142:143], 0.5 op_sel_hi:[1,0]
	v_pk_mul_f32 v[144:145], v[144:145], 0.5 op_sel_hi:[1,0]
	v_pk_mul_f32 v[146:147], v[146:147], 0.5 op_sel_hi:[1,0]
	v_pk_mul_f32 v[148:149], v[148:149], 0.5 op_sel_hi:[1,0]
	v_pk_mul_f32 v[150:151], v[150:151], 0.5 op_sel_hi:[1,0]
	v_pk_mul_f32 v[152:153], v[152:153], 0.5 op_sel_hi:[1,0]
	v_pk_mul_f32 v[154:155], v[154:155], 0.5 op_sel_hi:[1,0]
	v_pk_fma_f32 v[124:125], v[124:125], v[140:141], v[188:189]
	v_pk_fma_f32 v[126:127], v[126:127], v[142:143], v[190:191]
	v_pk_mul_f32 v[248:249], v[124:125], v[124:125]
	v_pk_fma_f32 v[248:249], v[126:127], v[126:127], v[248:249]
	v_pk_fma_f32 v[104:105], v[104:105], v[144:145], v[192:193]
	v_pk_fma_f32 v[106:107], v[106:107], v[146:147], v[194:195]
	v_pk_fma_f32 v[248:249], v[104:105], v[104:105], v[248:249]
	v_pk_fma_f32 v[248:249], v[106:107], v[106:107], v[248:249]
	v_pk_fma_f32 v[68:69], v[68:69], v[148:149], v[196:197]
	v_pk_fma_f32 v[70:71], v[70:71], v[150:151], v[198:199]
	v_pk_fma_f32 v[248:249], v[68:69], v[68:69], v[248:249]
	v_pk_fma_f32 v[248:249], v[70:71], v[70:71], v[248:249]
	v_pk_fma_f32 v[44:45], v[44:45], v[152:153], v[200:201]
	v_pk_fma_f32 v[46:47], v[46:47], v[154:155], v[202:203]
	v_pk_fma_f32 v[248:249], v[44:45], v[44:45], v[248:249]
	v_pk_fma_f32 v[248:249], v[46:47], v[46:47], v[248:249]
	global_store_dwordx4 v128, v[124:127], s[8:9]
	global_store_dwordx4 v128, v[104:107], s[8:9] offset:64
	global_store_dwordx4 v128, v[68:71], s[8:9] offset:512
	global_store_dwordx4 v128, v[44:47], s[8:9] offset:576
	v_add_f32_e32 v172, v248, v249
	v_pk_fma_f32 v[120:121], v[120:121], v[140:141], v[204:205]
	v_pk_fma_f32 v[122:123], v[122:123], v[142:143], v[206:207]
	v_pk_mul_f32 v[248:249], v[120:121], v[120:121]
	v_pk_fma_f32 v[248:249], v[122:123], v[122:123], v[248:249]
	v_pk_fma_f32 v[96:97], v[96:97], v[144:145], v[208:209]
	v_pk_fma_f32 v[98:99], v[98:99], v[146:147], v[210:211]
	v_pk_fma_f32 v[248:249], v[96:97], v[96:97], v[248:249]
	v_pk_fma_f32 v[248:249], v[98:99], v[98:99], v[248:249]
	v_pk_fma_f32 v[64:65], v[64:65], v[148:149], v[212:213]
	v_pk_fma_f32 v[66:67], v[66:67], v[150:151], v[214:215]
	v_pk_fma_f32 v[248:249], v[64:65], v[64:65], v[248:249]
	v_pk_fma_f32 v[248:249], v[66:67], v[66:67], v[248:249]
	v_pk_fma_f32 v[36:37], v[36:37], v[152:153], v[216:217]
	v_pk_fma_f32 v[38:39], v[38:39], v[154:155], v[218:219]
	v_pk_fma_f32 v[248:249], v[36:37], v[36:37], v[248:249]
	v_pk_fma_f32 v[248:249], v[38:39], v[38:39], v[248:249]
	global_store_dwordx4 v129, v[120:123], s[8:9]
	global_store_dwordx4 v129, v[96:99], s[8:9] offset:64
	global_store_dwordx4 v129, v[64:67], s[8:9] offset:512
	global_store_dwordx4 v129, v[36:39], s[8:9] offset:576
	v_add_f32_e32 v173, v248, v249
	s_nop 1
	global_load_dwordx4 v[188:191], v132, s[0:1]
	global_load_dwordx4 v[192:195], v132, s[0:1] offset:64
	global_load_dwordx4 v[196:199], v132, s[0:1] offset:512
	global_load_dwordx4 v[200:203], v132, s[0:1] offset:576
	global_load_dwordx4 v[204:207], v133, s[0:1]
	global_load_dwordx4 v[208:211], v133, s[0:1] offset:64
	global_load_dwordx4 v[212:215], v133, s[0:1] offset:512
	global_load_dwordx4 v[216:219], v133, s[0:1] offset:576
	s_waitcnt vmcnt(16)
	v_pk_fma_f32 v[116:117], v[116:117], v[140:141], v[156:157]
	v_pk_fma_f32 v[118:119], v[118:119], v[142:143], v[158:159]
	v_pk_mul_f32 v[248:249], v[116:117], v[116:117]
	v_pk_fma_f32 v[248:249], v[118:119], v[118:119], v[248:249]
	v_pk_fma_f32 v[88:89], v[88:89], v[144:145], v[160:161]
	v_pk_fma_f32 v[90:91], v[90:91], v[146:147], v[162:163]
	v_pk_fma_f32 v[248:249], v[88:89], v[88:89], v[248:249]
	v_pk_fma_f32 v[248:249], v[90:91], v[90:91], v[248:249]
	v_pk_fma_f32 v[52:53], v[52:53], v[148:149], v[164:165]
	v_pk_fma_f32 v[54:55], v[54:55], v[150:151], v[166:167]
	v_pk_fma_f32 v[248:249], v[52:53], v[52:53], v[248:249]
	v_pk_fma_f32 v[248:249], v[54:55], v[54:55], v[248:249]
	v_pk_fma_f32 v[28:29], v[28:29], v[152:153], v[168:169]
	v_pk_fma_f32 v[30:31], v[30:31], v[154:155], v[170:171]
	v_pk_fma_f32 v[248:249], v[28:29], v[28:29], v[248:249]
	v_pk_fma_f32 v[248:249], v[30:31], v[30:31], v[248:249]
	global_store_dwordx4 v130, v[116:119], s[8:9]
	global_store_dwordx4 v130, v[88:91], s[8:9] offset:64
	global_store_dwordx4 v130, v[52:55], s[8:9] offset:512
	global_store_dwordx4 v130, v[28:31], s[8:9] offset:576
	v_add_f32_e32 v174, v248, v249
	v_pk_fma_f32 v[112:113], v[112:113], v[140:141], v[232:233]
	v_pk_fma_f32 v[114:115], v[114:115], v[142:143], v[234:235]
	v_pk_mul_f32 v[248:249], v[112:113], v[112:113]
	v_pk_fma_f32 v[248:249], v[114:115], v[114:115], v[248:249]
	v_pk_fma_f32 v[80:81], v[80:81], v[144:145], v[236:237]
	v_pk_fma_f32 v[82:83], v[82:83], v[146:147], v[238:239]
	v_pk_fma_f32 v[248:249], v[80:81], v[80:81], v[248:249]
	v_pk_fma_f32 v[248:249], v[82:83], v[82:83], v[248:249]
	v_pk_fma_f32 v[48:49], v[48:49], v[148:149], v[240:241]
	v_pk_fma_f32 v[50:51], v[50:51], v[150:151], v[242:243]
	v_pk_fma_f32 v[248:249], v[48:49], v[48:49], v[248:249]
	v_pk_fma_f32 v[248:249], v[50:51], v[50:51], v[248:249]
	v_pk_fma_f32 v[20:21], v[20:21], v[152:153], v[244:245]
	v_pk_fma_f32 v[22:23], v[22:23], v[154:155], v[246:247]
	v_pk_fma_f32 v[248:249], v[20:21], v[20:21], v[248:249]
	v_pk_fma_f32 v[248:249], v[22:23], v[22:23], v[248:249]
	global_store_dwordx4 v131, v[112:115], s[8:9]
	global_store_dwordx4 v131, v[80:83], s[8:9] offset:64
	global_store_dwordx4 v131, v[48:51], s[8:9] offset:512
	global_store_dwordx4 v131, v[20:23], s[8:9] offset:576
	v_add_f32_e32 v175, v248, v249
	s_nop 1
	global_load_dwordx4 v[156:159], v134, s[0:1]
	global_load_dwordx4 v[160:163], v134, s[0:1] offset:64
	global_load_dwordx4 v[164:167], v134, s[0:1] offset:512
	global_load_dwordx4 v[168:171], v134, s[0:1] offset:576
	global_load_dwordx4 v[232:235], v135, s[0:1]
	global_load_dwordx4 v[236:239], v135, s[0:1] offset:64
	global_load_dwordx4 v[240:243], v135, s[0:1] offset:512
	global_load_dwordx4 v[244:247], v135, s[0:1] offset:576
	s_waitcnt vmcnt(16)
	v_pk_fma_f32 v[108:109], v[108:109], v[140:141], v[188:189]
	v_pk_fma_f32 v[110:111], v[110:111], v[142:143], v[190:191]
	v_pk_mul_f32 v[248:249], v[108:109], v[108:109]
	v_pk_fma_f32 v[248:249], v[110:111], v[110:111], v[248:249]
	v_pk_fma_f32 v[76:77], v[76:77], v[144:145], v[192:193]
	v_pk_fma_f32 v[78:79], v[78:79], v[146:147], v[194:195]
	v_pk_fma_f32 v[248:249], v[76:77], v[76:77], v[248:249]
	v_pk_fma_f32 v[248:249], v[78:79], v[78:79], v[248:249]
	v_pk_fma_f32 v[40:41], v[40:41], v[148:149], v[196:197]
	v_pk_fma_f32 v[42:43], v[42:43], v[150:151], v[198:199]
	v_pk_fma_f32 v[248:249], v[40:41], v[40:41], v[248:249]
	v_pk_fma_f32 v[248:249], v[42:43], v[42:43], v[248:249]
	v_pk_fma_f32 v[12:13], v[12:13], v[152:153], v[200:201]
	v_pk_fma_f32 v[14:15], v[14:15], v[154:155], v[202:203]
	v_pk_fma_f32 v[248:249], v[12:13], v[12:13], v[248:249]
	v_pk_fma_f32 v[248:249], v[14:15], v[14:15], v[248:249]
	global_store_dwordx4 v132, v[108:111], s[8:9]
	global_store_dwordx4 v132, v[76:79], s[8:9] offset:64
	global_store_dwordx4 v132, v[40:43], s[8:9] offset:512
	global_store_dwordx4 v132, v[12:15], s[8:9] offset:576
	v_add_f32_e32 v227, v248, v249
	v_pk_fma_f32 v[100:101], v[100:101], v[140:141], v[204:205]
	v_pk_fma_f32 v[102:103], v[102:103], v[142:143], v[206:207]
	v_pk_mul_f32 v[248:249], v[100:101], v[100:101]
	v_pk_fma_f32 v[248:249], v[102:103], v[102:103], v[248:249]
	v_pk_fma_f32 v[72:73], v[72:73], v[144:145], v[208:209]
	v_pk_fma_f32 v[74:75], v[74:75], v[146:147], v[210:211]
	v_pk_fma_f32 v[248:249], v[72:73], v[72:73], v[248:249]
	v_pk_fma_f32 v[248:249], v[74:75], v[74:75], v[248:249]
	v_pk_fma_f32 v[32:33], v[32:33], v[148:149], v[212:213]
	v_pk_fma_f32 v[34:35], v[34:35], v[150:151], v[214:215]
	v_pk_fma_f32 v[248:249], v[32:33], v[32:33], v[248:249]
	v_pk_fma_f32 v[248:249], v[34:35], v[34:35], v[248:249]
	v_pk_fma_f32 v[8:9], v[8:9], v[152:153], v[216:217]
	v_pk_fma_f32 v[10:11], v[10:11], v[154:155], v[218:219]
	v_pk_fma_f32 v[248:249], v[8:9], v[8:9], v[248:249]
	v_pk_fma_f32 v[248:249], v[10:11], v[10:11], v[248:249]
	global_store_dwordx4 v133, v[100:103], s[8:9]
	global_store_dwordx4 v133, v[72:75], s[8:9] offset:64
	global_store_dwordx4 v133, v[32:35], s[8:9] offset:512
	global_store_dwordx4 v133, v[8:11], s[8:9] offset:576
	v_add_f32_e32 v228, v248, v249
	s_waitcnt vmcnt(8)
	v_pk_fma_f32 v[92:93], v[92:93], v[140:141], v[156:157]
	v_pk_fma_f32 v[94:95], v[94:95], v[142:143], v[158:159]
	v_pk_mul_f32 v[248:249], v[92:93], v[92:93]
	v_pk_fma_f32 v[248:249], v[94:95], v[94:95], v[248:249]
	v_pk_fma_f32 v[60:61], v[60:61], v[144:145], v[160:161]
	v_pk_fma_f32 v[62:63], v[62:63], v[146:147], v[162:163]
	v_pk_fma_f32 v[248:249], v[60:61], v[60:61], v[248:249]
	v_pk_fma_f32 v[248:249], v[62:63], v[62:63], v[248:249]
	v_pk_fma_f32 v[24:25], v[24:25], v[148:149], v[164:165]
	v_pk_fma_f32 v[26:27], v[26:27], v[150:151], v[166:167]
	v_pk_fma_f32 v[248:249], v[24:25], v[24:25], v[248:249]
	v_pk_fma_f32 v[248:249], v[26:27], v[26:27], v[248:249]
	v_pk_fma_f32 v[4:5], v[4:5], v[152:153], v[168:169]
	v_pk_fma_f32 v[6:7], v[6:7], v[154:155], v[170:171]
	v_pk_fma_f32 v[248:249], v[4:5], v[4:5], v[248:249]
	v_pk_fma_f32 v[248:249], v[6:7], v[6:7], v[248:249]
	global_store_dwordx4 v134, v[92:95], s[8:9]
	global_store_dwordx4 v134, v[60:63], s[8:9] offset:64
	global_store_dwordx4 v134, v[24:27], s[8:9] offset:512
	global_store_dwordx4 v134, v[4:7], s[8:9] offset:576
	v_add_f32_e32 v229, v248, v249
	v_pk_fma_f32 v[84:85], v[84:85], v[140:141], v[232:233]
	v_pk_fma_f32 v[86:87], v[86:87], v[142:143], v[234:235]
	v_pk_mul_f32 v[248:249], v[84:85], v[84:85]
	v_pk_fma_f32 v[248:249], v[86:87], v[86:87], v[248:249]
	v_pk_fma_f32 v[56:57], v[56:57], v[144:145], v[236:237]
	v_pk_fma_f32 v[58:59], v[58:59], v[146:147], v[238:239]
	v_pk_fma_f32 v[248:249], v[56:57], v[56:57], v[248:249]
	v_pk_fma_f32 v[248:249], v[58:59], v[58:59], v[248:249]
	v_pk_fma_f32 v[16:17], v[16:17], v[148:149], v[240:241]
	v_pk_fma_f32 v[18:19], v[18:19], v[150:151], v[242:243]
	v_pk_fma_f32 v[248:249], v[16:17], v[16:17], v[248:249]
	v_pk_fma_f32 v[248:249], v[18:19], v[18:19], v[248:249]
	v_pk_fma_f32 v[0:1], v[0:1], v[152:153], v[244:245]
	v_pk_fma_f32 v[2:3], v[2:3], v[154:155], v[246:247]
	v_pk_fma_f32 v[248:249], v[0:1], v[0:1], v[248:249]
	v_pk_fma_f32 v[248:249], v[2:3], v[2:3], v[248:249]
	global_store_dwordx4 v135, v[84:87], s[8:9]
	global_store_dwordx4 v135, v[56:59], s[8:9] offset:64
	global_store_dwordx4 v135, v[16:19], s[8:9] offset:512
	global_store_dwordx4 v135, v[0:3], s[8:9] offset:576
	v_add_f32_e32 v231, v248, v249
	ds_bpermute_b32 v188, v137, v172
	ds_bpermute_b32 v189, v137, v173
	ds_bpermute_b32 v190, v137, v174
	ds_bpermute_b32 v191, v137, v175
	ds_bpermute_b32 v192, v137, v227
	ds_bpermute_b32 v193, v137, v228
	ds_bpermute_b32 v194, v137, v229
	ds_bpermute_b32 v195, v137, v231
	s_waitcnt lgkmcnt(0)
	v_add_f32_e32 v172, v172, v188
	v_add_f32_e32 v173, v173, v189
	v_add_f32_e32 v174, v174, v190
	v_add_f32_e32 v175, v175, v191
	v_add_f32_e32 v227, v227, v192
	v_add_f32_e32 v228, v228, v193
	v_add_f32_e32 v229, v229, v194
	v_add_f32_e32 v231, v231, v195
	ds_bpermute_b32 v188, v138, v172
	ds_bpermute_b32 v189, v138, v173
	ds_bpermute_b32 v190, v138, v174
	ds_bpermute_b32 v191, v138, v175
	ds_bpermute_b32 v192, v138, v227
	ds_bpermute_b32 v193, v138, v228
	ds_bpermute_b32 v194, v138, v229
	ds_bpermute_b32 v195, v138, v231
	s_waitcnt lgkmcnt(0)
	v_add_f32_e32 v172, v172, v188
	v_add_f32_e32 v173, v173, v189
	v_add_f32_e32 v174, v174, v190
	v_add_f32_e32 v175, v175, v191
	v_add_f32_e32 v227, v227, v192
	v_add_f32_e32 v228, v228, v193
	v_add_f32_e32 v229, v229, v194
	v_add_f32_e32 v231, v231, v195
	v_lshrrev_b32_e32 v140, 5, v223
	v_and_b32_e32 v140, 3, v140
	v_lshlrev_b32_e32 v142, 4, v221
	v_add_u32_e32 v142, 0x20400, v142
	v_lshl_add_u32 v141, v140, 2, v142
	v_lshl_add_u32 v144, s36, 8, v221
	v_lshlrev_b32_e32 v144, 4, v144
	v_mov_b32_e32 v143, s37
	v_lshl_add_u32 v143, v143, 2, v144
	s_mov_b64 exec, 0xffff
	ds_write_b32 v141, v172
	ds_write_b32 v141, v173 offset:256
	ds_write_b32 v141, v174 offset:512
	ds_write_b32 v141, v175 offset:768
	ds_write_b32 v141, v227 offset:2048
	ds_write_b32 v141, v228 offset:2304
	ds_write_b32 v141, v229 offset:2560
	ds_write_b32 v141, v231 offset:2816
	s_mov_b64 exec, -1
	s_waitcnt lgkmcnt(0)
	s_barrier
	ds_read_b128 v[156:159], v142
	ds_read_b128 v[160:163], v142 offset:256
	ds_read_b128 v[164:167], v142 offset:512
	ds_read_b128 v[168:171], v142 offset:768
	ds_read_b128 v[232:235], v142 offset:2048
	ds_read_b128 v[236:239], v142 offset:2304
	ds_read_b128 v[240:243], v142 offset:2560
	ds_read_b128 v[244:247], v142 offset:2816
	s_waitcnt lgkmcnt(0)
	v_add_f32_e32 v248, v156, v157
	v_add_f32_e32 v249, v158, v159
	v_add_f32_e32 v172, v248, v249
	v_add_f32_e32 v248, v160, v161
	v_add_f32_e32 v249, v162, v163
	v_add_f32_e32 v173, v248, v249
	v_add_f32_e32 v248, v164, v165
	v_add_f32_e32 v249, v166, v167
	v_add_f32_e32 v174, v248, v249
	v_add_f32_e32 v248, v168, v169
	v_add_f32_e32 v249, v170, v171
	v_add_f32_e32 v175, v248, v249
	v_add_f32_e32 v248, v232, v233
	v_add_f32_e32 v249, v234, v235
	v_add_f32_e32 v227, v248, v249
	v_add_f32_e32 v248, v236, v237
	v_add_f32_e32 v249, v238, v239
	v_add_f32_e32 v228, v248, v249
	v_add_f32_e32 v248, v240, v241
	v_add_f32_e32 v249, v242, v243
	v_add_f32_e32 v229, v248, v249
	v_add_f32_e32 v248, v244, v245
	v_add_f32_e32 v249, v246, v247
	v_add_f32_e32 v231, v248, v249
	v_readfirstlane_b32 s84, v140
	s_nop 0
	s_cmp_lg_u32 s84, 0
	s_cbranch_scc1 .Lfn_nosw_p2
	s_mov_b64 exec, 0xffff
	global_atomic_swap v143, v172, s[24:25]
	global_atomic_swap v143, v173, s[24:25] offset:256
	global_atomic_swap v143, v174, s[24:25] offset:512
	global_atomic_swap v143, v175, s[24:25] offset:768
	global_atomic_swap v143, v227, s[24:25] offset:2048
	global_atomic_swap v143, v228, s[24:25] offset:2304
	global_atomic_swap v143, v229, s[24:25] offset:2560
	global_atomic_swap v143, v231, s[24:25] offset:2816
	s_mov_b64 exec, -1
.Lfn_nosw_p2:
	s_waitcnt vmcnt(0)
	s_barrier
	v_cmp_eq_u32_e32 vcc, 0, v230
	s_and_saveexec_b64 s[82:83], vcc
	s_cbranch_execz .Lfn_meet_p2
	s_lshl_b32 s84, s36, 2
	v_mov_b32_e32 v248, 1
	v_mov_b32_e32 v249, s84
	s_mov_b32 s85, 0
	global_atomic_add v249, v248, s[26:27]
.Lfn_spin_p2:
	global_load_dword v248, v249, s[26:27] sc1
	s_waitcnt vmcnt(0)
	v_readfirstlane_b32 s84, v248
	s_add_i32 s85, s85, 1
	s_cmp_ge_u32 s84, 4
	s_cbranch_scc1 .Lfn_meet_p2
	s_sleep 1
	s_cmp_lt_u32 s85, 0x8000
	s_cbranch_scc1 .Lfn_spin_p2
.Lfn_meet_p2:
	s_or_b64 exec, exec, s[82:83]
	s_barrier
	global_load_dwordx4 v[156:159], v144, s[24:25] sc1
	global_load_dwordx4 v[160:163], v144, s[24:25] offset:256 sc1
	global_load_dwordx4 v[164:167], v144, s[24:25] offset:512 sc1
	global_load_dwordx4 v[168:171], v144, s[24:25] offset:768 sc1
	global_load_dwordx4 v[232:235], v144, s[24:25] offset:2048 sc1
	global_load_dwordx4 v[236:239], v144, s[24:25] offset:2304 sc1
	global_load_dwordx4 v[240:243], v144, s[24:25] offset:2560 sc1
	global_load_dwordx4 v[244:247], v144, s[24:25] offset:2816 sc1
	s_waitcnt vmcnt(0)
	v_add_f32_e32 v248, v156, v157
	v_add_f32_e32 v249, v158, v159
	v_add_f32_e32 v146, v248, v249
	v_add_f32_e32 v248, v160, v161
	v_add_f32_e32 v249, v162, v163
	v_add_f32_e32 v147, v248, v249
	v_add_f32_e32 v248, v164, v165
	v_add_f32_e32 v249, v166, v167
	v_add_f32_e32 v148, v248, v249
	v_add_f32_e32 v248, v168, v169
	v_add_f32_e32 v249, v170, v171
	v_add_f32_e32 v149, v248, v249
	v_add_f32_e32 v248, v232, v233
	v_add_f32_e32 v249, v234, v235
	v_add_f32_e32 v150, v248, v249
	v_add_f32_e32 v248, v236, v237
	v_add_f32_e32 v249, v238, v239
	v_add_f32_e32 v151, v248, v249
	v_add_f32_e32 v248, v240, v241
	v_add_f32_e32 v249, v242, v243
	v_add_f32_e32 v152, v248, v249
	v_add_f32_e32 v248, v244, v245
	v_add_f32_e32 v249, v246, v247
	v_add_f32_e32 v153, v248, v249
	global_load_dwordx4 v[188:191], v136, s[22:23]
	global_load_dwordx4 v[192:195], v136, s[22:23] offset:64
	global_load_dwordx4 v[196:199], v136, s[22:23] offset:512
	global_load_dwordx4 v[200:203], v136, s[22:23] offset:576
	global_load_dwordx4 v[156:159], v136, s[76:77]
	global_load_dwordx4 v[160:163], v136, s[76:77] offset:64
	global_load_dwordx4 v[164:167], v136, s[76:77] offset:512
	global_load_dwordx4 v[168:171], v136, s[76:77] offset:576
	global_load_dwordx4 v[232:235], v136, s[78:79]
	global_load_dwordx4 v[236:239], v136, s[78:79] offset:64
	global_load_dwordx4 v[240:243], v136, s[78:79] offset:512
	global_load_dwordx4 v[244:247], v136, s[78:79] offset:576
	v_mov_b32_e32 v229, 0x358637bd
	v_mov_b32_e32 v231, 0x260
	s_mov_b32 s39, 0xf800000
	v_fmamk_f32 v146, v146, 0x3a800000, v229
	v_mul_f32_e32 v172, 0x4f800000, v146
	v_cmp_gt_f32_e32 vcc, s39, v146
	s_nop 1
	v_cndmask_b32_e32 v146, v146, v172, vcc
	v_sqrt_f32_e32 v173, v146
	s_nop 1
	v_add_u32_e32 v174, -1, v173
	v_add_u32_e32 v175, 1, v173
	v_fma_f32 v227, -v174, v173, v146
	v_fma_f32 v228, -v175, v173, v146
	v_cmp_ge_f32_e64 s[12:13], 0, v227
	s_nop 1
	v_cndmask_b32_e64 v173, v173, v174, s[12:13]
	v_cmp_lt_f32_e64 s[12:13], 0, v228
	s_nop 1
	v_cndmask_b32_e64 v173, v173, v175, s[12:13]
	v_mul_f32_e32 v174, 0x37800000, v173
	v_cndmask_b32_e32 v173, v173, v174, vcc
	v_cmp_class_f32_e32 vcc, v146, v231
	s_nop 1
	v_cndmask_b32_e32 v146, v173, v146, vcc
	v_div_scale_f32 v172, s[12:13], v146, v146, 1.0
	v_rcp_f32_e32 v173, v172
	v_div_scale_f32 v174, vcc, 1.0, v146, 1.0
	v_fma_f32 v175, -v172, v173, 1.0
	v_fmac_f32_e32 v173, v175, v173
	v_mul_f32_e32 v175, v174, v173
	v_fma_f32 v227, -v172, v175, v174
	v_fmac_f32_e32 v175, v227, v173
	v_fma_f32 v172, -v172, v175, v174
	v_div_fmas_f32 v175, v172, v173, v175
	v_div_fixup_f32 v204, v175, v146, 1.0
	v_fmamk_f32 v147, v147, 0x3a800000, v229
	v_mul_f32_e32 v172, 0x4f800000, v147
	v_cmp_gt_f32_e32 vcc, s39, v147
	s_nop 1
	v_cndmask_b32_e32 v147, v147, v172, vcc
	v_sqrt_f32_e32 v173, v147
	s_nop 1
	v_add_u32_e32 v174, -1, v173
	v_add_u32_e32 v175, 1, v173
	v_fma_f32 v227, -v174, v173, v147
	v_fma_f32 v228, -v175, v173, v147
	v_cmp_ge_f32_e64 s[12:13], 0, v227
	s_nop 1
	v_cndmask_b32_e64 v173, v173, v174, s[12:13]
	v_cmp_lt_f32_e64 s[12:13], 0, v228
	s_nop 1
	v_cndmask_b32_e64 v173, v173, v175, s[12:13]
	v_mul_f32_e32 v174, 0x37800000, v173
	v_cndmask_b32_e32 v173, v173, v174, vcc
	v_cmp_class_f32_e32 vcc, v147, v231
	s_nop 1
	v_cndmask_b32_e32 v147, v173, v147, vcc
	v_div_scale_f32 v172, s[12:13], v147, v147, 1.0
	v_rcp_f32_e32 v173, v172
	v_div_scale_f32 v174, vcc, 1.0, v147, 1.0
	v_fma_f32 v175, -v172, v173, 1.0
	v_fmac_f32_e32 v173, v175, v173
	v_mul_f32_e32 v175, v174, v173
	v_fma_f32 v227, -v172, v175, v174
	v_fmac_f32_e32 v175, v227, v173
	v_fma_f32 v172, -v172, v175, v174
	v_div_fmas_f32 v175, v172, v173, v175
	v_div_fixup_f32 v206, v175, v147, 1.0
	v_fmamk_f32 v148, v148, 0x3a800000, v229
	v_mul_f32_e32 v172, 0x4f800000, v148
	v_cmp_gt_f32_e32 vcc, s39, v148
	s_nop 1
	v_cndmask_b32_e32 v148, v148, v172, vcc
	v_sqrt_f32_e32 v173, v148
	s_nop 1
	v_add_u32_e32 v174, -1, v173
	v_add_u32_e32 v175, 1, v173
	v_fma_f32 v227, -v174, v173, v148
	v_fma_f32 v228, -v175, v173, v148
	v_cmp_ge_f32_e64 s[12:13], 0, v227
	s_nop 1
	v_cndmask_b32_e64 v173, v173, v174, s[12:13]
	v_cmp_lt_f32_e64 s[12:13], 0, v228
	s_nop 1
	v_cndmask_b32_e64 v173, v173, v175, s[12:13]
	v_mul_f32_e32 v174, 0x37800000, v173
	v_cndmask_b32_e32 v173, v173, v174, vcc
	v_cmp_class_f32_e32 vcc, v148, v231
	s_nop 1
	v_cndmask_b32_e32 v148, v173, v148, vcc
	v_div_scale_f32 v172, s[12:13], v148, v148, 1.0
	v_rcp_f32_e32 v173, v172
	v_div_scale_f32 v174, vcc, 1.0, v148, 1.0
	v_fma_f32 v175, -v172, v173, 1.0
	v_fmac_f32_e32 v173, v175, v173
	v_mul_f32_e32 v175, v174, v173
	v_fma_f32 v227, -v172, v175, v174
	v_fmac_f32_e32 v175, v227, v173
	v_fma_f32 v172, -v172, v175, v174
	v_div_fmas_f32 v175, v172, v173, v175
	v_div_fixup_f32 v208, v175, v148, 1.0
	v_fmamk_f32 v149, v149, 0x3a800000, v229
	v_mul_f32_e32 v172, 0x4f800000, v149
	v_cmp_gt_f32_e32 vcc, s39, v149
	s_nop 1
	v_cndmask_b32_e32 v149, v149, v172, vcc
	v_sqrt_f32_e32 v173, v149
	s_nop 1
	v_add_u32_e32 v174, -1, v173
	v_add_u32_e32 v175, 1, v173
	v_fma_f32 v227, -v174, v173, v149
	v_fma_f32 v228, -v175, v173, v149
	v_cmp_ge_f32_e64 s[12:13], 0, v227
	s_nop 1
	v_cndmask_b32_e64 v173, v173, v174, s[12:13]
	v_cmp_lt_f32_e64 s[12:13], 0, v228
	s_nop 1
	v_cndmask_b32_e64 v173, v173, v175, s[12:13]
	v_mul_f32_e32 v174, 0x37800000, v173
	v_cndmask_b32_e32 v173, v173, v174, vcc
	v_cmp_class_f32_e32 vcc, v149, v231
	s_nop 1
	v_cndmask_b32_e32 v149, v173, v149, vcc
	v_div_scale_f32 v172, s[12:13], v149, v149, 1.0
	v_rcp_f32_e32 v173, v172
	v_div_scale_f32 v174, vcc, 1.0, v149, 1.0
	v_fma_f32 v175, -v172, v173, 1.0
	v_fmac_f32_e32 v173, v175, v173
	v_mul_f32_e32 v175, v174, v173
	v_fma_f32 v227, -v172, v175, v174
	v_fmac_f32_e32 v175, v227, v173
	v_fma_f32 v172, -v172, v175, v174
	v_div_fmas_f32 v175, v172, v173, v175
	v_div_fixup_f32 v210, v175, v149, 1.0
	v_fmamk_f32 v150, v150, 0x3a800000, v229
	v_mul_f32_e32 v172, 0x4f800000, v150
	v_cmp_gt_f32_e32 vcc, s39, v150
	s_nop 1
	v_cndmask_b32_e32 v150, v150, v172, vcc
	v_sqrt_f32_e32 v173, v150
	s_nop 1
	v_add_u32_e32 v174, -1, v173
	v_add_u32_e32 v175, 1, v173
	v_fma_f32 v227, -v174, v173, v150
	v_fma_f32 v228, -v175, v173, v150
	v_cmp_ge_f32_e64 s[12:13], 0, v227
	s_nop 1
	v_cndmask_b32_e64 v173, v173, v174, s[12:13]
	v_cmp_lt_f32_e64 s[12:13], 0, v228
	s_nop 1
	v_cndmask_b32_e64 v173, v173, v175, s[12:13]
	v_mul_f32_e32 v174, 0x37800000, v173
	v_cndmask_b32_e32 v173, v173, v174, vcc
	v_cmp_class_f32_e32 vcc, v150, v231
	s_nop 1
	v_cndmask_b32_e32 v150, v173, v150, vcc
	v_div_scale_f32 v172, s[12:13], v150, v150, 1.0
	v_rcp_f32_e32 v173, v172
	v_div_scale_f32 v174, vcc, 1.0, v150, 1.0
	v_fma_f32 v175, -v172, v173, 1.0
	v_fmac_f32_e32 v173, v175, v173
	v_mul_f32_e32 v175, v174, v173
	v_fma_f32 v227, -v172, v175, v174
	v_fmac_f32_e32 v175, v227, v173
	v_fma_f32 v172, -v172, v175, v174
	v_div_fmas_f32 v175, v172, v173, v175
	v_div_fixup_f32 v212, v175, v150, 1.0
	v_fmamk_f32 v151, v151, 0x3a800000, v229
	v_mul_f32_e32 v172, 0x4f800000, v151
	v_cmp_gt_f32_e32 vcc, s39, v151
	s_nop 1
	v_cndmask_b32_e32 v151, v151, v172, vcc
	v_sqrt_f32_e32 v173, v151
	s_nop 1
	v_add_u32_e32 v174, -1, v173
	v_add_u32_e32 v175, 1, v173
	v_fma_f32 v227, -v174, v173, v151
	v_fma_f32 v228, -v175, v173, v151
	v_cmp_ge_f32_e64 s[12:13], 0, v227
	s_nop 1
	v_cndmask_b32_e64 v173, v173, v174, s[12:13]
	v_cmp_lt_f32_e64 s[12:13], 0, v228
	s_nop 1
	v_cndmask_b32_e64 v173, v173, v175, s[12:13]
	v_mul_f32_e32 v174, 0x37800000, v173
	v_cndmask_b32_e32 v173, v173, v174, vcc
	v_cmp_class_f32_e32 vcc, v151, v231
	s_nop 1
	v_cndmask_b32_e32 v151, v173, v151, vcc
	v_div_scale_f32 v172, s[12:13], v151, v151, 1.0
	v_rcp_f32_e32 v173, v172
	v_div_scale_f32 v174, vcc, 1.0, v151, 1.0
	v_fma_f32 v175, -v172, v173, 1.0
	v_fmac_f32_e32 v173, v175, v173
	v_mul_f32_e32 v175, v174, v173
	v_fma_f32 v227, -v172, v175, v174
	v_fmac_f32_e32 v175, v227, v173
	v_fma_f32 v172, -v172, v175, v174
	v_div_fmas_f32 v175, v172, v173, v175
	v_div_fixup_f32 v214, v175, v151, 1.0
	v_fmamk_f32 v152, v152, 0x3a800000, v229
	v_mul_f32_e32 v172, 0x4f800000, v152
	v_cmp_gt_f32_e32 vcc, s39, v152
	s_nop 1
	v_cndmask_b32_e32 v152, v152, v172, vcc
	v_sqrt_f32_e32 v173, v152
	s_nop 1
	v_add_u32_e32 v174, -1, v173
	v_add_u32_e32 v175, 1, v173
	v_fma_f32 v227, -v174, v173, v152
	v_fma_f32 v228, -v175, v173, v152
	v_cmp_ge_f32_e64 s[12:13], 0, v227
	s_nop 1
	v_cndmask_b32_e64 v173, v173, v174, s[12:13]
	v_cmp_lt_f32_e64 s[12:13], 0, v228
	s_nop 1
	v_cndmask_b32_e64 v173, v173, v175, s[12:13]
	v_mul_f32_e32 v174, 0x37800000, v173
	v_cndmask_b32_e32 v173, v173, v174, vcc
	v_cmp_class_f32_e32 vcc, v152, v231
	s_nop 1
	v_cndmask_b32_e32 v152, v173, v152, vcc
	v_div_scale_f32 v172, s[12:13], v152, v152, 1.0
	v_rcp_f32_e32 v173, v172
	v_div_scale_f32 v174, vcc, 1.0, v152, 1.0
	v_fma_f32 v175, -v172, v173, 1.0
	v_fmac_f32_e32 v173, v175, v173
	v_mul_f32_e32 v175, v174, v173
	v_fma_f32 v227, -v172, v175, v174
	v_fmac_f32_e32 v175, v227, v173
	v_fma_f32 v172, -v172, v175, v174
	v_div_fmas_f32 v175, v172, v173, v175
	v_div_fixup_f32 v216, v175, v152, 1.0
	v_fmamk_f32 v153, v153, 0x3a800000, v229
	v_mul_f32_e32 v172, 0x4f800000, v153
	v_cmp_gt_f32_e32 vcc, s39, v153
	s_nop 1
	v_cndmask_b32_e32 v153, v153, v172, vcc
	v_sqrt_f32_e32 v173, v153
	s_nop 1
	v_add_u32_e32 v174, -1, v173
	v_add_u32_e32 v175, 1, v173
	v_fma_f32 v227, -v174, v173, v153
	v_fma_f32 v228, -v175, v173, v153
	v_cmp_ge_f32_e64 s[12:13], 0, v227
	s_nop 1
	v_cndmask_b32_e64 v173, v173, v174, s[12:13]
	v_cmp_lt_f32_e64 s[12:13], 0, v228
	s_nop 1
	v_cndmask_b32_e64 v173, v173, v175, s[12:13]
	v_mul_f32_e32 v174, 0x37800000, v173
	v_cndmask_b32_e32 v173, v173, v174, vcc
	v_cmp_class_f32_e32 vcc, v153, v231
	s_nop 1
	v_cndmask_b32_e32 v153, v173, v153, vcc
	v_div_scale_f32 v172, s[12:13], v153, v153, 1.0
	v_rcp_f32_e32 v173, v172
	v_div_scale_f32 v174, vcc, 1.0, v153, 1.0
	v_fma_f32 v175, -v172, v173, 1.0
	v_fmac_f32_e32 v173, v175, v173
	v_mul_f32_e32 v175, v174, v173
	v_fma_f32 v227, -v172, v175, v174
	v_fmac_f32_e32 v175, v227, v173
	v_fma_f32 v172, -v172, v175, v174
	v_div_fmas_f32 v175, v172, v173, v175
	v_div_fixup_f32 v218, v175, v153, 1.0
	v_lshrrev_b32_e32 v128, 1, v128
	v_lshrrev_b32_e32 v129, 1, v129
	v_lshrrev_b32_e32 v130, 1, v130
	v_lshrrev_b32_e32 v131, 1, v131
	v_lshrrev_b32_e32 v132, 1, v132
	v_lshrrev_b32_e32 v133, 1, v133
	v_lshrrev_b32_e32 v134, 1, v134
	v_lshrrev_b32_e32 v135, 1, v135
	s_waitcnt vmcnt(0)
	v_pk_add_f32 v[156:157], v[156:157], 1.0 op_sel_hi:[1,0]
	v_pk_add_f32 v[158:159], v[158:159], 1.0 op_sel_hi:[1,0]
	v_pk_add_f32 v[160:161], v[160:161], 1.0 op_sel_hi:[1,0]
	v_pk_add_f32 v[162:163], v[162:163], 1.0 op_sel_hi:[1,0]
	v_pk_add_f32 v[164:165], v[164:165], 1.0 op_sel_hi:[1,0]
	v_pk_add_f32 v[166:167], v[166:167], 1.0 op_sel_hi:[1,0]
	v_pk_add_f32 v[168:169], v[168:169], 1.0 op_sel_hi:[1,0]
	v_pk_add_f32 v[170:171], v[170:171], 1.0 op_sel_hi:[1,0]
	v_and_b32_e32 v144, 16, v230
	v_cmp_ne_u32_e64 s[80:81], 0, v144
	v_mov_b32_e32 v145, 24
	s_nop 0
	v_cndmask_b32_e64 v144, 0, v145, s[80:81]
	v_add_u32_e32 v128, v128, v144
	v_add_u32_e32 v129, v129, v144
	v_add_u32_e32 v130, v130, v144
	v_add_u32_e32 v131, v131, v144
	v_add_u32_e32 v132, v132, v144
	v_add_u32_e32 v133, v133, v144
	v_add_u32_e32 v134, v134, v144
	v_add_u32_e32 v135, v135, v144
	v_pk_mul_f32 v[124:125], v[124:125], v[204:205] op_sel_hi:[1,0]
	v_pk_mul_f32 v[126:127], v[126:127], v[204:205] op_sel_hi:[1,0]
	v_pk_mul_f32 v[124:125], v[188:189], v[124:125]
	v_pk_mul_f32 v[126:127], v[190:191], v[126:127]
	v_pk_fma_f32 v[124:125], v[156:157], v[124:125], v[232:233]
	v_pk_fma_f32 v[126:127], v[158:159], v[126:127], v[234:235]
	v_cvt_pk_bf16_f32 v124, v124, v125
	v_cvt_pk_bf16_f32 v125, v126, v127
	v_pk_mul_f32 v[104:105], v[104:105], v[204:205] op_sel_hi:[1,0]
	v_pk_mul_f32 v[106:107], v[106:107], v[204:205] op_sel_hi:[1,0]
	v_pk_mul_f32 v[104:105], v[192:193], v[104:105]
	v_pk_mul_f32 v[106:107], v[194:195], v[106:107]
	v_pk_fma_f32 v[104:105], v[160:161], v[104:105], v[236:237]
	v_pk_fma_f32 v[106:107], v[162:163], v[106:107], v[238:239]
	v_cvt_pk_bf16_f32 v104, v104, v105
	v_cvt_pk_bf16_f32 v105, v106, v107
	v_pk_mul_f32 v[68:69], v[68:69], v[204:205] op_sel_hi:[1,0]
	v_pk_mul_f32 v[70:71], v[70:71], v[204:205] op_sel_hi:[1,0]
	v_pk_mul_f32 v[68:69], v[196:197], v[68:69]
	v_pk_mul_f32 v[70:71], v[198:199], v[70:71]
	v_pk_fma_f32 v[68:69], v[164:165], v[68:69], v[240:241]
	v_pk_fma_f32 v[70:71], v[166:167], v[70:71], v[242:243]
	v_cvt_pk_bf16_f32 v68, v68, v69
	v_cvt_pk_bf16_f32 v69, v70, v71
	v_pk_mul_f32 v[44:45], v[44:45], v[204:205] op_sel_hi:[1,0]
	v_pk_mul_f32 v[46:47], v[46:47], v[204:205] op_sel_hi:[1,0]
	v_pk_mul_f32 v[44:45], v[200:201], v[44:45]
	v_pk_mul_f32 v[46:47], v[202:203], v[46:47]
	v_pk_fma_f32 v[44:45], v[168:169], v[44:45], v[244:245]
	v_pk_fma_f32 v[46:47], v[170:171], v[46:47], v[246:247]
	v_cvt_pk_bf16_f32 v44, v44, v45
	v_cvt_pk_bf16_f32 v45, v46, v47
	v_cndmask_b32_e64 v146, v104, v124, s[80:81]
	v_cndmask_b32_e64 v147, v105, v125, s[80:81]
	ds_bpermute_b32 v148, v137, v146
	ds_bpermute_b32 v149, v137, v147
	v_cndmask_b32_e64 v150, v44, v68, s[80:81]
	v_cndmask_b32_e64 v151, v45, v69, s[80:81]
	ds_bpermute_b32 v152, v137, v150
	ds_bpermute_b32 v153, v137, v151
	s_waitcnt lgkmcnt(0)
	v_cndmask_b32_e64 v126, v148, v104, s[80:81]
	v_cndmask_b32_e64 v127, v149, v105, s[80:81]
	v_cndmask_b32_e64 v124, v124, v148, s[80:81]
	v_cndmask_b32_e64 v125, v125, v149, s[80:81]
	global_store_dwordx4 v128, v[124:127], s[74:75]
	v_cndmask_b32_e64 v70, v152, v44, s[80:81]
	v_cndmask_b32_e64 v71, v153, v45, s[80:81]
	v_cndmask_b32_e64 v68, v68, v152, s[80:81]
	v_cndmask_b32_e64 v69, v69, v153, s[80:81]
	global_store_dwordx4 v128, v[68:71], s[74:75] offset:256
	v_pk_mul_f32 v[120:121], v[120:121], v[206:207] op_sel_hi:[1,0]
	v_pk_mul_f32 v[122:123], v[122:123], v[206:207] op_sel_hi:[1,0]
	v_pk_mul_f32 v[120:121], v[188:189], v[120:121]
	v_pk_mul_f32 v[122:123], v[190:191], v[122:123]
	v_pk_fma_f32 v[120:121], v[156:157], v[120:121], v[232:233]
	v_pk_fma_f32 v[122:123], v[158:159], v[122:123], v[234:235]
	v_cvt_pk_bf16_f32 v120, v120, v121
	v_cvt_pk_bf16_f32 v121, v122, v123
	v_pk_mul_f32 v[96:97], v[96:97], v[206:207] op_sel_hi:[1,0]
	v_pk_mul_f32 v[98:99], v[98:99], v[206:207] op_sel_hi:[1,0]
	v_pk_mul_f32 v[96:97], v[192:193], v[96:97]
	v_pk_mul_f32 v[98:99], v[194:195], v[98:99]
	v_pk_fma_f32 v[96:97], v[160:161], v[96:97], v[236:237]
	v_pk_fma_f32 v[98:99], v[162:163], v[98:99], v[238:239]
	v_cvt_pk_bf16_f32 v96, v96, v97
	v_cvt_pk_bf16_f32 v97, v98, v99
	v_pk_mul_f32 v[64:65], v[64:65], v[206:207] op_sel_hi:[1,0]
	v_pk_mul_f32 v[66:67], v[66:67], v[206:207] op_sel_hi:[1,0]
	v_pk_mul_f32 v[64:65], v[196:197], v[64:65]
	v_pk_mul_f32 v[66:67], v[198:199], v[66:67]
	v_pk_fma_f32 v[64:65], v[164:165], v[64:65], v[240:241]
	v_pk_fma_f32 v[66:67], v[166:167], v[66:67], v[242:243]
	v_cvt_pk_bf16_f32 v64, v64, v65
	v_cvt_pk_bf16_f32 v65, v66, v67
	v_pk_mul_f32 v[36:37], v[36:37], v[206:207] op_sel_hi:[1,0]
	v_pk_mul_f32 v[38:39], v[38:39], v[206:207] op_sel_hi:[1,0]
	v_pk_mul_f32 v[36:37], v[200:201], v[36:37]
	v_pk_mul_f32 v[38:39], v[202:203], v[38:39]
	v_pk_fma_f32 v[36:37], v[168:169], v[36:37], v[244:245]
	v_pk_fma_f32 v[38:39], v[170:171], v[38:39], v[246:247]
	v_cvt_pk_bf16_f32 v36, v36, v37
	v_cvt_pk_bf16_f32 v37, v38, v39
	v_cndmask_b32_e64 v146, v96, v120, s[80:81]
	v_cndmask_b32_e64 v147, v97, v121, s[80:81]
	ds_bpermute_b32 v148, v137, v146
	ds_bpermute_b32 v149, v137, v147
	v_cndmask_b32_e64 v150, v36, v64, s[80:81]
	v_cndmask_b32_e64 v151, v37, v65, s[80:81]
	ds_bpermute_b32 v152, v137, v150
	ds_bpermute_b32 v153, v137, v151
	s_waitcnt lgkmcnt(0)
	v_cndmask_b32_e64 v122, v148, v96, s[80:81]
	v_cndmask_b32_e64 v123, v149, v97, s[80:81]
	v_cndmask_b32_e64 v120, v120, v148, s[80:81]
	v_cndmask_b32_e64 v121, v121, v149, s[80:81]
	global_store_dwordx4 v129, v[120:123], s[74:75]
	v_cndmask_b32_e64 v66, v152, v36, s[80:81]
	v_cndmask_b32_e64 v67, v153, v37, s[80:81]
	v_cndmask_b32_e64 v64, v64, v152, s[80:81]
	v_cndmask_b32_e64 v65, v65, v153, s[80:81]
	global_store_dwordx4 v129, v[64:67], s[74:75] offset:256
	v_pk_mul_f32 v[116:117], v[116:117], v[208:209] op_sel_hi:[1,0]
	v_pk_mul_f32 v[118:119], v[118:119], v[208:209] op_sel_hi:[1,0]
	v_pk_mul_f32 v[116:117], v[188:189], v[116:117]
	v_pk_mul_f32 v[118:119], v[190:191], v[118:119]
	v_pk_fma_f32 v[116:117], v[156:157], v[116:117], v[232:233]
	v_pk_fma_f32 v[118:119], v[158:159], v[118:119], v[234:235]
	v_cvt_pk_bf16_f32 v116, v116, v117
	v_cvt_pk_bf16_f32 v117, v118, v119
	v_pk_mul_f32 v[88:89], v[88:89], v[208:209] op_sel_hi:[1,0]
	v_pk_mul_f32 v[90:91], v[90:91], v[208:209] op_sel_hi:[1,0]
	v_pk_mul_f32 v[88:89], v[192:193], v[88:89]
	v_pk_mul_f32 v[90:91], v[194:195], v[90:91]
	v_pk_fma_f32 v[88:89], v[160:161], v[88:89], v[236:237]
	v_pk_fma_f32 v[90:91], v[162:163], v[90:91], v[238:239]
	v_cvt_pk_bf16_f32 v88, v88, v89
	v_cvt_pk_bf16_f32 v89, v90, v91
	v_pk_mul_f32 v[52:53], v[52:53], v[208:209] op_sel_hi:[1,0]
	v_pk_mul_f32 v[54:55], v[54:55], v[208:209] op_sel_hi:[1,0]
	v_pk_mul_f32 v[52:53], v[196:197], v[52:53]
	v_pk_mul_f32 v[54:55], v[198:199], v[54:55]
	v_pk_fma_f32 v[52:53], v[164:165], v[52:53], v[240:241]
	v_pk_fma_f32 v[54:55], v[166:167], v[54:55], v[242:243]
	v_cvt_pk_bf16_f32 v52, v52, v53
	v_cvt_pk_bf16_f32 v53, v54, v55
	v_pk_mul_f32 v[28:29], v[28:29], v[208:209] op_sel_hi:[1,0]
	v_pk_mul_f32 v[30:31], v[30:31], v[208:209] op_sel_hi:[1,0]
	v_pk_mul_f32 v[28:29], v[200:201], v[28:29]
	v_pk_mul_f32 v[30:31], v[202:203], v[30:31]
	v_pk_fma_f32 v[28:29], v[168:169], v[28:29], v[244:245]
	v_pk_fma_f32 v[30:31], v[170:171], v[30:31], v[246:247]
	v_cvt_pk_bf16_f32 v28, v28, v29
	v_cvt_pk_bf16_f32 v29, v30, v31
	v_cndmask_b32_e64 v146, v88, v116, s[80:81]
	v_cndmask_b32_e64 v147, v89, v117, s[80:81]
	ds_bpermute_b32 v148, v137, v146
	ds_bpermute_b32 v149, v137, v147
	v_cndmask_b32_e64 v150, v28, v52, s[80:81]
	v_cndmask_b32_e64 v151, v29, v53, s[80:81]
	ds_bpermute_b32 v152, v137, v150
	ds_bpermute_b32 v153, v137, v151
	s_waitcnt lgkmcnt(0)
	v_cndmask_b32_e64 v118, v148, v88, s[80:81]
	v_cndmask_b32_e64 v119, v149, v89, s[80:81]
	v_cndmask_b32_e64 v116, v116, v148, s[80:81]
	v_cndmask_b32_e64 v117, v117, v149, s[80:81]
	global_store_dwordx4 v130, v[116:119], s[74:75]
	v_cndmask_b32_e64 v54, v152, v28, s[80:81]
	v_cndmask_b32_e64 v55, v153, v29, s[80:81]
	v_cndmask_b32_e64 v52, v52, v152, s[80:81]
	v_cndmask_b32_e64 v53, v53, v153, s[80:81]
	global_store_dwordx4 v130, v[52:55], s[74:75] offset:256
	v_pk_mul_f32 v[112:113], v[112:113], v[210:211] op_sel_hi:[1,0]
	v_pk_mul_f32 v[114:115], v[114:115], v[210:211] op_sel_hi:[1,0]
	v_pk_mul_f32 v[112:113], v[188:189], v[112:113]
	v_pk_mul_f32 v[114:115], v[190:191], v[114:115]
	v_pk_fma_f32 v[112:113], v[156:157], v[112:113], v[232:233]
	v_pk_fma_f32 v[114:115], v[158:159], v[114:115], v[234:235]
	v_cvt_pk_bf16_f32 v112, v112, v113
	v_cvt_pk_bf16_f32 v113, v114, v115
	v_pk_mul_f32 v[80:81], v[80:81], v[210:211] op_sel_hi:[1,0]
	v_pk_mul_f32 v[82:83], v[82:83], v[210:211] op_sel_hi:[1,0]
	v_pk_mul_f32 v[80:81], v[192:193], v[80:81]
	v_pk_mul_f32 v[82:83], v[194:195], v[82:83]
	v_pk_fma_f32 v[80:81], v[160:161], v[80:81], v[236:237]
	v_pk_fma_f32 v[82:83], v[162:163], v[82:83], v[238:239]
	v_cvt_pk_bf16_f32 v80, v80, v81
	v_cvt_pk_bf16_f32 v81, v82, v83
	v_pk_mul_f32 v[48:49], v[48:49], v[210:211] op_sel_hi:[1,0]
	v_pk_mul_f32 v[50:51], v[50:51], v[210:211] op_sel_hi:[1,0]
	v_pk_mul_f32 v[48:49], v[196:197], v[48:49]
	v_pk_mul_f32 v[50:51], v[198:199], v[50:51]
	v_pk_fma_f32 v[48:49], v[164:165], v[48:49], v[240:241]
	v_pk_fma_f32 v[50:51], v[166:167], v[50:51], v[242:243]
	v_cvt_pk_bf16_f32 v48, v48, v49
	v_cvt_pk_bf16_f32 v49, v50, v51
	v_pk_mul_f32 v[20:21], v[20:21], v[210:211] op_sel_hi:[1,0]
	v_pk_mul_f32 v[22:23], v[22:23], v[210:211] op_sel_hi:[1,0]
	v_pk_mul_f32 v[20:21], v[200:201], v[20:21]
	v_pk_mul_f32 v[22:23], v[202:203], v[22:23]
	v_pk_fma_f32 v[20:21], v[168:169], v[20:21], v[244:245]
	v_pk_fma_f32 v[22:23], v[170:171], v[22:23], v[246:247]
	v_cvt_pk_bf16_f32 v20, v20, v21
	v_cvt_pk_bf16_f32 v21, v22, v23
	v_cndmask_b32_e64 v146, v80, v112, s[80:81]
	v_cndmask_b32_e64 v147, v81, v113, s[80:81]
	ds_bpermute_b32 v148, v137, v146
	ds_bpermute_b32 v149, v137, v147
	v_cndmask_b32_e64 v150, v20, v48, s[80:81]
	v_cndmask_b32_e64 v151, v21, v49, s[80:81]
	ds_bpermute_b32 v152, v137, v150
	ds_bpermute_b32 v153, v137, v151
	s_waitcnt lgkmcnt(0)
	v_cndmask_b32_e64 v114, v148, v80, s[80:81]
	v_cndmask_b32_e64 v115, v149, v81, s[80:81]
	v_cndmask_b32_e64 v112, v112, v148, s[80:81]
	v_cndmask_b32_e64 v113, v113, v149, s[80:81]
	global_store_dwordx4 v131, v[112:115], s[74:75]
	v_cndmask_b32_e64 v50, v152, v20, s[80:81]
	v_cndmask_b32_e64 v51, v153, v21, s[80:81]
	v_cndmask_b32_e64 v48, v48, v152, s[80:81]
	v_cndmask_b32_e64 v49, v49, v153, s[80:81]
	global_store_dwordx4 v131, v[48:51], s[74:75] offset:256
	v_pk_mul_f32 v[108:109], v[108:109], v[212:213] op_sel_hi:[1,0]
	v_pk_mul_f32 v[110:111], v[110:111], v[212:213] op_sel_hi:[1,0]
	v_pk_mul_f32 v[108:109], v[188:189], v[108:109]
	v_pk_mul_f32 v[110:111], v[190:191], v[110:111]
	v_pk_fma_f32 v[108:109], v[156:157], v[108:109], v[232:233]
	v_pk_fma_f32 v[110:111], v[158:159], v[110:111], v[234:235]
	v_cvt_pk_bf16_f32 v108, v108, v109
	v_cvt_pk_bf16_f32 v109, v110, v111
	v_pk_mul_f32 v[76:77], v[76:77], v[212:213] op_sel_hi:[1,0]
	v_pk_mul_f32 v[78:79], v[78:79], v[212:213] op_sel_hi:[1,0]
	v_pk_mul_f32 v[76:77], v[192:193], v[76:77]
	v_pk_mul_f32 v[78:79], v[194:195], v[78:79]
	v_pk_fma_f32 v[76:77], v[160:161], v[76:77], v[236:237]
	v_pk_fma_f32 v[78:79], v[162:163], v[78:79], v[238:239]
	v_cvt_pk_bf16_f32 v76, v76, v77
	v_cvt_pk_bf16_f32 v77, v78, v79
	v_pk_mul_f32 v[40:41], v[40:41], v[212:213] op_sel_hi:[1,0]
	v_pk_mul_f32 v[42:43], v[42:43], v[212:213] op_sel_hi:[1,0]
	v_pk_mul_f32 v[40:41], v[196:197], v[40:41]
	v_pk_mul_f32 v[42:43], v[198:199], v[42:43]
	v_pk_fma_f32 v[40:41], v[164:165], v[40:41], v[240:241]
	v_pk_fma_f32 v[42:43], v[166:167], v[42:43], v[242:243]
	v_cvt_pk_bf16_f32 v40, v40, v41
	v_cvt_pk_bf16_f32 v41, v42, v43
	v_pk_mul_f32 v[12:13], v[12:13], v[212:213] op_sel_hi:[1,0]
	v_pk_mul_f32 v[14:15], v[14:15], v[212:213] op_sel_hi:[1,0]
	v_pk_mul_f32 v[12:13], v[200:201], v[12:13]
	v_pk_mul_f32 v[14:15], v[202:203], v[14:15]
	v_pk_fma_f32 v[12:13], v[168:169], v[12:13], v[244:245]
	v_pk_fma_f32 v[14:15], v[170:171], v[14:15], v[246:247]
	v_cvt_pk_bf16_f32 v12, v12, v13
	v_cvt_pk_bf16_f32 v13, v14, v15
	v_cndmask_b32_e64 v146, v76, v108, s[80:81]
	v_cndmask_b32_e64 v147, v77, v109, s[80:81]
	ds_bpermute_b32 v148, v137, v146
	ds_bpermute_b32 v149, v137, v147
	v_cndmask_b32_e64 v150, v12, v40, s[80:81]
	v_cndmask_b32_e64 v151, v13, v41, s[80:81]
	ds_bpermute_b32 v152, v137, v150
	ds_bpermute_b32 v153, v137, v151
	s_waitcnt lgkmcnt(0)
	v_cndmask_b32_e64 v110, v148, v76, s[80:81]
	v_cndmask_b32_e64 v111, v149, v77, s[80:81]
	v_cndmask_b32_e64 v108, v108, v148, s[80:81]
	v_cndmask_b32_e64 v109, v109, v149, s[80:81]
	global_store_dwordx4 v132, v[108:111], s[74:75]
	v_cndmask_b32_e64 v42, v152, v12, s[80:81]
	v_cndmask_b32_e64 v43, v153, v13, s[80:81]
	v_cndmask_b32_e64 v40, v40, v152, s[80:81]
	v_cndmask_b32_e64 v41, v41, v153, s[80:81]
	global_store_dwordx4 v132, v[40:43], s[74:75] offset:256
	v_pk_mul_f32 v[100:101], v[100:101], v[214:215] op_sel_hi:[1,0]
	v_pk_mul_f32 v[102:103], v[102:103], v[214:215] op_sel_hi:[1,0]
	v_pk_mul_f32 v[100:101], v[188:189], v[100:101]
	v_pk_mul_f32 v[102:103], v[190:191], v[102:103]
	v_pk_fma_f32 v[100:101], v[156:157], v[100:101], v[232:233]
	v_pk_fma_f32 v[102:103], v[158:159], v[102:103], v[234:235]
	v_cvt_pk_bf16_f32 v100, v100, v101
	v_cvt_pk_bf16_f32 v101, v102, v103
	v_pk_mul_f32 v[72:73], v[72:73], v[214:215] op_sel_hi:[1,0]
	v_pk_mul_f32 v[74:75], v[74:75], v[214:215] op_sel_hi:[1,0]
	v_pk_mul_f32 v[72:73], v[192:193], v[72:73]
	v_pk_mul_f32 v[74:75], v[194:195], v[74:75]
	v_pk_fma_f32 v[72:73], v[160:161], v[72:73], v[236:237]
	v_pk_fma_f32 v[74:75], v[162:163], v[74:75], v[238:239]
	v_cvt_pk_bf16_f32 v72, v72, v73
	v_cvt_pk_bf16_f32 v73, v74, v75
	v_pk_mul_f32 v[32:33], v[32:33], v[214:215] op_sel_hi:[1,0]
	v_pk_mul_f32 v[34:35], v[34:35], v[214:215] op_sel_hi:[1,0]
	v_pk_mul_f32 v[32:33], v[196:197], v[32:33]
	v_pk_mul_f32 v[34:35], v[198:199], v[34:35]
	v_pk_fma_f32 v[32:33], v[164:165], v[32:33], v[240:241]
	v_pk_fma_f32 v[34:35], v[166:167], v[34:35], v[242:243]
	v_cvt_pk_bf16_f32 v32, v32, v33
	v_cvt_pk_bf16_f32 v33, v34, v35
	v_pk_mul_f32 v[8:9], v[8:9], v[214:215] op_sel_hi:[1,0]
	v_pk_mul_f32 v[10:11], v[10:11], v[214:215] op_sel_hi:[1,0]
	v_pk_mul_f32 v[8:9], v[200:201], v[8:9]
	v_pk_mul_f32 v[10:11], v[202:203], v[10:11]
	v_pk_fma_f32 v[8:9], v[168:169], v[8:9], v[244:245]
	v_pk_fma_f32 v[10:11], v[170:171], v[10:11], v[246:247]
	v_cvt_pk_bf16_f32 v8, v8, v9
	v_cvt_pk_bf16_f32 v9, v10, v11
	v_cndmask_b32_e64 v146, v72, v100, s[80:81]
	v_cndmask_b32_e64 v147, v73, v101, s[80:81]
	ds_bpermute_b32 v148, v137, v146
	ds_bpermute_b32 v149, v137, v147
	v_cndmask_b32_e64 v150, v8, v32, s[80:81]
	v_cndmask_b32_e64 v151, v9, v33, s[80:81]
	ds_bpermute_b32 v152, v137, v150
	ds_bpermute_b32 v153, v137, v151
	s_waitcnt lgkmcnt(0)
	v_cndmask_b32_e64 v102, v148, v72, s[80:81]
	v_cndmask_b32_e64 v103, v149, v73, s[80:81]
	v_cndmask_b32_e64 v100, v100, v148, s[80:81]
	v_cndmask_b32_e64 v101, v101, v149, s[80:81]
	global_store_dwordx4 v133, v[100:103], s[74:75]
	v_cndmask_b32_e64 v34, v152, v8, s[80:81]
	v_cndmask_b32_e64 v35, v153, v9, s[80:81]
	v_cndmask_b32_e64 v32, v32, v152, s[80:81]
	v_cndmask_b32_e64 v33, v33, v153, s[80:81]
	global_store_dwordx4 v133, v[32:35], s[74:75] offset:256
	v_pk_mul_f32 v[92:93], v[92:93], v[216:217] op_sel_hi:[1,0]
	v_pk_mul_f32 v[94:95], v[94:95], v[216:217] op_sel_hi:[1,0]
	v_pk_mul_f32 v[92:93], v[188:189], v[92:93]
	v_pk_mul_f32 v[94:95], v[190:191], v[94:95]
	v_pk_fma_f32 v[92:93], v[156:157], v[92:93], v[232:233]
	v_pk_fma_f32 v[94:95], v[158:159], v[94:95], v[234:235]
	v_cvt_pk_bf16_f32 v92, v92, v93
	v_cvt_pk_bf16_f32 v93, v94, v95
	v_pk_mul_f32 v[60:61], v[60:61], v[216:217] op_sel_hi:[1,0]
	v_pk_mul_f32 v[62:63], v[62:63], v[216:217] op_sel_hi:[1,0]
	v_pk_mul_f32 v[60:61], v[192:193], v[60:61]
	v_pk_mul_f32 v[62:63], v[194:195], v[62:63]
	v_pk_fma_f32 v[60:61], v[160:161], v[60:61], v[236:237]
	v_pk_fma_f32 v[62:63], v[162:163], v[62:63], v[238:239]
	v_cvt_pk_bf16_f32 v60, v60, v61
	v_cvt_pk_bf16_f32 v61, v62, v63
	v_pk_mul_f32 v[24:25], v[24:25], v[216:217] op_sel_hi:[1,0]
	v_pk_mul_f32 v[26:27], v[26:27], v[216:217] op_sel_hi:[1,0]
	v_pk_mul_f32 v[24:25], v[196:197], v[24:25]
	v_pk_mul_f32 v[26:27], v[198:199], v[26:27]
	v_pk_fma_f32 v[24:25], v[164:165], v[24:25], v[240:241]
	v_pk_fma_f32 v[26:27], v[166:167], v[26:27], v[242:243]
	v_cvt_pk_bf16_f32 v24, v24, v25
	v_cvt_pk_bf16_f32 v25, v26, v27
	v_pk_mul_f32 v[4:5], v[4:5], v[216:217] op_sel_hi:[1,0]
	v_pk_mul_f32 v[6:7], v[6:7], v[216:217] op_sel_hi:[1,0]
	v_pk_mul_f32 v[4:5], v[200:201], v[4:5]
	v_pk_mul_f32 v[6:7], v[202:203], v[6:7]
	v_pk_fma_f32 v[4:5], v[168:169], v[4:5], v[244:245]
	v_pk_fma_f32 v[6:7], v[170:171], v[6:7], v[246:247]
	v_cvt_pk_bf16_f32 v4, v4, v5
	v_cvt_pk_bf16_f32 v5, v6, v7
	v_cndmask_b32_e64 v146, v60, v92, s[80:81]
	v_cndmask_b32_e64 v147, v61, v93, s[80:81]
	ds_bpermute_b32 v148, v137, v146
	ds_bpermute_b32 v149, v137, v147
	v_cndmask_b32_e64 v150, v4, v24, s[80:81]
	v_cndmask_b32_e64 v151, v5, v25, s[80:81]
	ds_bpermute_b32 v152, v137, v150
	ds_bpermute_b32 v153, v137, v151
	s_waitcnt lgkmcnt(0)
	v_cndmask_b32_e64 v94, v148, v60, s[80:81]
	v_cndmask_b32_e64 v95, v149, v61, s[80:81]
	v_cndmask_b32_e64 v92, v92, v148, s[80:81]
	v_cndmask_b32_e64 v93, v93, v149, s[80:81]
	global_store_dwordx4 v134, v[92:95], s[74:75]
	v_cndmask_b32_e64 v26, v152, v4, s[80:81]
	v_cndmask_b32_e64 v27, v153, v5, s[80:81]
	v_cndmask_b32_e64 v24, v24, v152, s[80:81]
	v_cndmask_b32_e64 v25, v25, v153, s[80:81]
	global_store_dwordx4 v134, v[24:27], s[74:75] offset:256
	v_pk_mul_f32 v[84:85], v[84:85], v[218:219] op_sel_hi:[1,0]
	v_pk_mul_f32 v[86:87], v[86:87], v[218:219] op_sel_hi:[1,0]
	v_pk_mul_f32 v[84:85], v[188:189], v[84:85]
	v_pk_mul_f32 v[86:87], v[190:191], v[86:87]
	v_pk_fma_f32 v[84:85], v[156:157], v[84:85], v[232:233]
	v_pk_fma_f32 v[86:87], v[158:159], v[86:87], v[234:235]
	v_cvt_pk_bf16_f32 v84, v84, v85
	v_cvt_pk_bf16_f32 v85, v86, v87
	v_pk_mul_f32 v[56:57], v[56:57], v[218:219] op_sel_hi:[1,0]
	v_pk_mul_f32 v[58:59], v[58:59], v[218:219] op_sel_hi:[1,0]
	v_pk_mul_f32 v[56:57], v[192:193], v[56:57]
	v_pk_mul_f32 v[58:59], v[194:195], v[58:59]
	v_pk_fma_f32 v[56:57], v[160:161], v[56:57], v[236:237]
	v_pk_fma_f32 v[58:59], v[162:163], v[58:59], v[238:239]
	v_cvt_pk_bf16_f32 v56, v56, v57
	v_cvt_pk_bf16_f32 v57, v58, v59
	v_pk_mul_f32 v[16:17], v[16:17], v[218:219] op_sel_hi:[1,0]
	v_pk_mul_f32 v[18:19], v[18:19], v[218:219] op_sel_hi:[1,0]
	v_pk_mul_f32 v[16:17], v[196:197], v[16:17]
	v_pk_mul_f32 v[18:19], v[198:199], v[18:19]
	v_pk_fma_f32 v[16:17], v[164:165], v[16:17], v[240:241]
	v_pk_fma_f32 v[18:19], v[166:167], v[18:19], v[242:243]
	v_cvt_pk_bf16_f32 v16, v16, v17
	v_cvt_pk_bf16_f32 v17, v18, v19
	v_pk_mul_f32 v[0:1], v[0:1], v[218:219] op_sel_hi:[1,0]
	v_pk_mul_f32 v[2:3], v[2:3], v[218:219] op_sel_hi:[1,0]
	v_pk_mul_f32 v[0:1], v[200:201], v[0:1]
	v_pk_mul_f32 v[2:3], v[202:203], v[2:3]
	v_pk_fma_f32 v[0:1], v[168:169], v[0:1], v[244:245]
	v_pk_fma_f32 v[2:3], v[170:171], v[2:3], v[246:247]
	v_cvt_pk_bf16_f32 v0, v0, v1
	v_cvt_pk_bf16_f32 v1, v2, v3
	v_cndmask_b32_e64 v146, v56, v84, s[80:81]
	v_cndmask_b32_e64 v147, v57, v85, s[80:81]
	ds_bpermute_b32 v148, v137, v146
	ds_bpermute_b32 v149, v137, v147
	v_cndmask_b32_e64 v150, v0, v16, s[80:81]
	v_cndmask_b32_e64 v151, v1, v17, s[80:81]
	ds_bpermute_b32 v152, v137, v150
	ds_bpermute_b32 v153, v137, v151
	s_waitcnt lgkmcnt(0)
	v_cndmask_b32_e64 v86, v148, v56, s[80:81]
	v_cndmask_b32_e64 v87, v149, v57, s[80:81]
	v_cndmask_b32_e64 v84, v84, v148, s[80:81]
	v_cndmask_b32_e64 v85, v85, v149, s[80:81]
	global_store_dwordx4 v135, v[84:87], s[74:75]
	v_cndmask_b32_e64 v18, v152, v0, s[80:81]
	v_cndmask_b32_e64 v19, v153, v1, s[80:81]
	v_cndmask_b32_e64 v16, v16, v152, s[80:81]
	v_cndmask_b32_e64 v17, v17, v153, s[80:81]
	global_store_dwordx4 v135, v[16:19], s[74:75] offset:256
	s_mov_b64 s[34:35], -1
	s_and_b64 vcc, exec, s[4:5]
	s_cbranch_vccnz .LBB0_346
	s_andn2_b64 vcc, exec, s[14:15]
	s_cbranch_vccnz .LBB0_345
	s_barrier
	s_branch .LBB0_345
